# selected-block loops: back-edge rotated, next-iteration scalar chain and prefetch addresses computed before the loop-back barrier
# speedup vs baseline: 1.0001x; 1.0001x over previous
; DI void nsa_wg_unit(const Args& a, int l, int b, int g, int tb, unsigned char* lds, int tid_in, bool stage) {
;     ...
;       while (j >= 0) {
;           rem &= rem - 1ull; const int nj = rem ? (int)__builtin_ctzll(rem) : -1;
;           if (nj >= 0) { kreg = *(const u32x4*)(kgb + (size_t)(64 * nj) * ZP * 2 + koff); vreg = *(const u32x4*)(vgb + (size_t)(64 * nj) * 2 + voff); }
.Lsel1_ld:
	s_cmp_eq_u32 s32, 0
	s_cbranch_scc1 .Lsel1_ldb
	global_load_dwordx4 v[96:99], v[48:49], off
	global_load_dwordx4 v[100:103], v[50:51], off
	s_branch .LBB0_169

; DI void nsa_wg_unit(const Args& a, int l, int b, int g, int tb, unsigned char* lds, int tid_in, bool stage) {
;     ...
;       while (j >= 0) {
;           rem &= rem - 1ull; const int nj = rem ? (int)__builtin_ctzll(rem) : -1;
;           if (nj >= 0) { kreg = *(const u32x4*)(kgb + (size_t)(64 * nj) * ZP * 2 + koff); vreg = *(const u32x4*)(vgb + (size_t)(64 * nj) * 2 + voff); }
;           if ((myu >> j) & 1ull) {
;               const bool on = ((j < 32) ? (sel_lo[0] >> j) & 1u : (sel_hi[0] >> (j - 32)) & 1u) != 0u;
;               attn_block64(st, qf, kfl + bi * KR_SZ, vfl + bi * VR_SZ, KR_PB, VR_PB, cref[1], on, j == jt, MaskCausal{tk[0]}, 64 * j, h); }
;           if (nj >= 0) { const int nb = bi ^ 1; *(u32x4*)(lds + AL_KR + nb * KR_SZ + srow * KR_PB + sch * 16) = kreg; u32x2* d = (u32x2*)(lds + AL_VR + nb * VR_SZ + srow * VR_PB + sch * 16); u32x2 lo2, hi2; lo2.x = vreg.x; lo2.y = vreg.y; hi2.x = vreg.z; hi2.y = vreg.w; d[0] = lo2; d[1] = hi2; }
;           __syncthreads();
;           j = nj; bi ^= 1; } }
.LBB0_177:
	s_andn2_b64 vcc, exec, s[78:79]
	s_cbranch_vccz .Lsel1_exit
	s_mov_b64 s[94:95], s[80:81]
	s_add_u32 s78, s84, -1
	s_addc_u32 s79, s85, -1
	s_and_b64 s[84:85], s[78:79], s[84:85]
	s_cmp_eq_u64 s[84:85], 0
	s_cselect_b64 s[78:79], -1, 0
	s_cmp_lg_u64 s[84:85], 0
	s_cselect_b64 s[86:87], -1, 0
	s_ff1_i32_b64 s80, s[84:85]
	s_add_u32 s100, s84, -1
	s_addc_u32 s101, s85, -1
	s_and_b64 s[100:101], s[100:101], s[84:85]
	s_cmp_eq_u64 s[100:101], 0
	s_cbranch_scc1 .Lsel1_rot0
	s_ff1_i32_b64 s98, s[100:101]
	s_mov_b32 s99, 0
	s_mul_i32 s88, s98, 0x88c00
	s_mov_b32 s89, 0
	s_lshl_b64 vcc, s[98:99], 7
	v_lshl_add_u64 v[48:49], v[144:145], 0, s[88:89]
	v_lshl_add_u64 v[50:51], v[146:147], 0, vcc
	s_waitcnt lgkmcnt(0)
	s_barrier
	s_branch .Lsel1_ld
.Lsel1_rot0:
	s_waitcnt lgkmcnt(0)
	s_barrier
	s_branch .LBB0_169
.Lsel1_exit:
	s_waitcnt lgkmcnt(0)
	s_barrier
.LBB0_179:
	v_readlane_b32 s36, v254, 63
	v_readlane_b32 s40, v255, 2
	v_readlane_b32 s42, v254, 61
	v_readlane_b32 s46, v254, 58
	s_mov_b64 s[0:1], 0
	s_movk_i32 s22, 0x90
	s_movk_i32 s23, 0x3cf
	s_mov_b32 s25, 0x42800000
	v_readlane_b32 s26, v253, 27
	s_movk_i32 s27, 0x88
	v_readlane_b32 s28, v253, 28
	s_mov_b32 s29, s2
	v_readlane_b32 s34, v255, 1
	v_readlane_b32 s37, v255, 0
	s_mov_b64 s[38:39], s[82:83]
	v_readlane_b32 s41, v255, 3
	v_readlane_b32 s43, v254, 62
	v_readlane_b32 s44, v254, 60
	v_readlane_b32 s47, v254, 59
	s_branch .LBB0_181

; DI void nsa_wg_unit(const Args& a, int l, int b, int g, int tb, unsigned char* lds, int tid_in, bool stage) {
;     ...
;       while (j >= 0) {
;           rem &= rem - 1ull; const int nj = rem ? (int)__builtin_ctzll(rem) : -1;
;           if (nj >= 0) { kreg = *(const u32x4*)(kgb + (size_t)(64 * nj) * ZP * 2 + koff); vreg = *(const u32x4*)(vgb + (size_t)(64 * nj) * 2 + voff); }
;           if ((myu >> j) & 1ull) {
;               const bool on = ((j < 32) ? (sel_lo[0] >> j) & 1u : (sel_hi[0] >> (j - 32)) & 1u) != 0u;
;               attn_block64(st, qf, kfl + bi * KR_SZ, vfl + bi * VR_SZ, KR_PB, VR_PB, cref[1], on, j == jt, MaskCausal{tk[0]}, 64 * j, h); }
;           if (nj >= 0) { const int nb = bi ^ 1; *(u32x4*)(lds + AL_KR + nb * KR_SZ + srow * KR_PB + sch * 16) = kreg; u32x2* d = (u32x2*)(lds + AL_VR + nb * VR_SZ + srow * VR_PB + sch * 16); u32x2 lo2, hi2; lo2.x = vreg.x; lo2.y = vreg.y; hi2.x = vreg.z; hi2.y = vreg.w; d[0] = lo2; d[1] = hi2; }
;           __syncthreads();
;           j = nj; bi ^= 1; } }
.LBB0_252:
	s_andn2_b64 vcc, exec, s[82:83]
	s_cbranch_vccz .Lsel2_exit
	s_mov_b64 s[86:87], s[80:81]
	s_add_u32 s82, s78, -1
	s_addc_u32 s83, s79, -1
	s_and_b64 s[78:79], s[82:83], s[78:79]
	s_cmp_eq_u64 s[78:79], 0
	s_cselect_b64 s[82:83], -1, 0
	s_cmp_lg_u64 s[78:79], 0
	s_cselect_b64 s[84:85], -1, 0
	s_ff1_i32_b64 s80, s[78:79]
	s_add_u32 s100, s78, -1
	s_addc_u32 s101, s79, -1
	s_and_b64 s[100:101], s[100:101], s[78:79]
	s_cmp_eq_u64 s[100:101], 0
	s_cbranch_scc1 .Lsel2_rot0
	s_ff1_i32_b64 s98, s[100:101]
	s_mov_b32 s99, 0
	s_mul_i32 s94, s98, 0x88c00
	s_mov_b32 s95, 0
	s_lshl_b64 s[88:89], s[98:99], 7
	v_lshl_add_u64 v[48:49], v[144:145], 0, s[94:95]
	v_lshl_add_u64 v[50:51], v[146:147], 0, s[88:89]
	s_waitcnt lgkmcnt(0)
	s_barrier
	s_branch .Lsel2_ld

; DI void nsa_wg_unit(const Args& a, int l, int b, int g, int tb, unsigned char* lds, int tid_in, bool stage) {
;     ...
;     { float sc[NRT]; const float lt = st.l[0] + __shfl_xor(st.l[0], 32); sc[0] = lt > 0.f ? gt[0][1] / lt : 0.f; attn_flush<false>(st, sc, orow); }
;     attn_reset(st);
;     { const unsigned koff = (unsigned)(srow * ZP + sch * 8) * 2u, voff = (unsigned)(srow * SEQ + sch * 8) * 2u; const char* kgb = (const char*)(zb + C_KV + 4 * 128 + g * 64); const char* vgb = (const char*)VWT;
;       int j = tb - 8 < 0 ? 0 : tb - 8, bi = 0; u32x4 kreg, vreg;
.Lsel2_exit:
	s_waitcnt lgkmcnt(0)
	s_barrier
.LBB0_254:
	s_mov_b64 s[0:1], 0
	s_movk_i32 s22, 0x90
	s_mov_b32 s25, 0x42800000
	v_readlane_b32 s26, v253, 27
	s_movk_i32 s27, 0x88
	v_readlane_b32 s28, v253, 28
	s_mov_b64 s[30:31], 0x88c00
	s_mov_b32 s35, s2
	v_readlane_b32 s2, v254, 63
	v_readlane_b32 s45, v255, 1
	v_readlane_b32 s46, v255, 2
	s_branch .LBB0_257
